# grid barrier spin loops poll without s_sleep between flag loads
# baseline (speedup 1.0000x reference)
.LBB0_1027:
	s_and_b32 s22, s4, 0xff
	s_mov_b64 s[20:21], -1
	s_cmp_lg_u32 s22, 0
	s_mov_b64 s[24:25], -1
	s_nop 0
	s_cbranch_scc0 .LBB0_1030
	s_and_b64 vcc, exec, s[24:25]
	s_cbranch_vccz .LBB0_1026
